# stagger (g mod 4) x ~7 us: four phases, span 21 us
# baseline (speedup 1.0000x reference)
; __device__ __forceinline__ void xcd_barrier(const XcdBarrier& b) {
;     ...
;     __syncthreads();
; __global__ void __launch_bounds__(NWAVES * 64, 2) fwd_kernel(Args args) {
;     ...
;         if (ph + 1 < args.ph_hi || rep + 1 < nrep) { if (args.ph_hi > 1000) grid.sync(); else xcd_barrier(xb); } else __syncthreads();
.LBB0_486:
	s_or_b64 exec, exec, s[26:27]
	s_cmp_eq_u32 s10, 1
	s_cbranch_scc0 stg_skip
	s_and_b32 s2, s89, 3
	s_lshl_b32 s2, s2, 1
